# v47 + progressive vmcnt waits on the 16 residual loads in G2/G4 (EpiRes) epilogues
# speedup vs baseline: 1.0150x; 1.0012x over previous
; __device__ __forceinline__ unsigned long long f2ss(float v) { return (unsigned long long)(v * 16777216.0f); }
; __device__ __forceinline__ u32x4 pack8(f32x4 v0, f32x4 v1) { u32x4 w; w.x = cvt_pk_bf16(v0[0], v0[1]); w.y = cvt_pk_bf16(v0[2], v0[3]); w.z = cvt_pk_bf16(v1[0], v1[1]); w.w = cvt_pk_bf16(v1[2], v1[3]); return w; }
;     __device__ __forceinline__ void operator()(const f32x4 (&acc)[2][2][4][2], const Unit& u, int wr, int wc, int fr, int fq, const Pre&) const {
;         const int row0 = u.pm * BM + wr * 64 + fr, col0 = u.pn * BM + wc * 32 + 8 * fq;
;         typedef __attribute__((address_space(1))) u32x4 gu32x4;
;         u32x4 bwv[2][4][2];
; #pragma unroll
;         for (int ai = 0; ai < 2; ++ai)
; #pragma unroll
;             for (int m = 0; m < 4; ++m)
; #pragma unroll
;                 for (int bj = 0; bj < 2; ++bj) bwv[ai][m][bj] = *(const gu32x4*)(hb + (size_t)(row0 + ai * HALF + m * 16) * 1024 + col0 + bj * HALF);
; #pragma unroll
;         for (int ai = 0; ai < 2; ++ai)
; #pragma unroll
;             for (int m = 0; m < 4; ++m) { const int row = row0 + ai * HALF + m * 16; const size_t off = (size_t)row * 1024 + col0; float sq = 0.f;
; #pragma unroll
;                 for (int bj = 0; bj < 2; ++bj) { const u32x4 bw = bwv[ai][m][bj];
;                     const f32x4 b0 = (f32x4){__uint_as_float(bw.x << 16), __uint_as_float(bw.x & 0xffff0000u), __uint_as_float(bw.y << 16), __uint_as_float(bw.y & 0xffff0000u)};
;                     const f32x4 b1 = (f32x4){__uint_as_float(bw.z << 16), __uint_as_float(bw.z & 0xffff0000u), __uint_as_float(bw.w << 16), __uint_as_float(bw.w & 0xffff0000u)};
;                     const f32x4 v0 = acc[ai][bj][m][0] + b0, v1 = acc[ai][bj][m][1] + b1;
;                     *(gu32x4*)(hb + off + bj * HALF) = pack8(v0, v1);
;                     sq += (v0[0] * v0[0] + v0[1] * v0[1]) + (v0[2] * v0[2] + v0[3] * v0[3]) + (v1[0] * v1[0] + v1[1] * v1[1]) + (v1[2] * v1[2] + v1[3] * v1[3]); }
;                 sq += __shfl_xor(sq, 16); sq += __shfl_xor(sq, 32); if (fq == 0) atomicAdd(ssn + row, f2ss(sq)); }
.LBB0_115:
	v_lshl_or_b32 v210, s36, 8, v241
	v_lshl_add_u32 v226, s4, 8, v145
	v_ashrrev_i32_e32 v211, 31, v210
	v_lshlrev_b64 v[228:229], 1, v[210:211]
	v_ashrrev_i32_e32 v227, 31, v226
	v_lshl_add_u64 v[112:113], s[28:29], 0, v[228:229]
	v_lshlrev_b64 v[230:231], 11, v[226:227]
	v_lshl_add_u64 v[114:115], v[112:113], 0, v[230:231]
	global_load_dwordx4 v[244:247], v[114:115], off
	global_load_dwordx4 v[192:195], v[114:115], off offset:256
	v_or_b32_e32 v114, 16, v226
	v_ashrrev_i32_e32 v115, 31, v114
	v_lshlrev_b64 v[224:225], 11, v[114:115]
	v_lshl_add_u64 v[114:115], v[112:113], 0, v[224:225]
	global_load_dwordx4 v[188:191], v[114:115], off
	global_load_dwordx4 v[184:187], v[114:115], off offset:256
	v_or_b32_e32 v114, 32, v226
	v_ashrrev_i32_e32 v115, 31, v114
	v_lshlrev_b64 v[222:223], 11, v[114:115]
	v_lshl_add_u64 v[114:115], v[112:113], 0, v[222:223]
	global_load_dwordx4 v[180:183], v[114:115], off
	global_load_dwordx4 v[176:179], v[114:115], off offset:256
	v_or_b32_e32 v114, 48, v226
	v_ashrrev_i32_e32 v115, 31, v114
	s_mov_b64 s[4:5], 0x40000
	v_lshlrev_b64 v[220:221], 11, v[114:115]
	v_lshl_add_u64 v[218:219], v[230:231], 0, s[4:5]
	s_mov_b64 s[4:5], 0x48000
	v_lshl_add_u64 v[114:115], v[112:113], 0, v[220:221]
	v_lshl_add_u64 v[216:217], v[230:231], 0, s[4:5]
	s_mov_b64 s[4:5], 0x50000
	global_load_dwordx4 v[172:175], v[114:115], off
	global_load_dwordx4 v[164:167], v[114:115], off offset:256
	v_lshl_add_u64 v[114:115], v[112:113], 0, v[218:219]
	v_lshl_add_u64 v[214:215], v[230:231], 0, s[4:5]
	s_mov_b64 s[4:5], 0x58000
	global_load_dwordx4 v[156:159], v[114:115], off
	global_load_dwordx4 v[152:155], v[114:115], off offset:256
	v_lshl_add_u64 v[114:115], v[112:113], 0, v[216:217]
	v_lshl_add_u64 v[212:213], v[230:231], 0, s[4:5]
	global_load_dwordx4 v[140:143], v[114:115], off
	global_load_dwordx4 v[132:135], v[114:115], off offset:256
	v_lshl_add_u64 v[114:115], v[112:113], 0, v[214:215]
	v_lshl_add_u64 v[112:113], v[112:113], 0, v[212:213]
	global_load_dwordx4 v[124:127], v[114:115], off
	global_load_dwordx4 v[116:119], v[114:115], off offset:256
	global_load_dwordx4 v[120:123], v[112:113], off
	s_nop 0
	global_load_dwordx4 v[112:115], v[112:113], off offset:256
	v_lshl_add_u64 v[230:231], s[28:29], 0, v[230:231]
	v_lshl_add_u64 v[228:229], v[230:231], 0, v[228:229]
	s_waitcnt vmcnt(15)
	v_lshlrev_b32_e32 v248, 16, v244
	v_and_b32_e32 v249, 0xffff0000, v244
	v_lshlrev_b32_e32 v244, 16, v245
	v_and_b32_e32 v245, 0xffff0000, v245
	v_lshlrev_b32_e32 v250, 16, v246
	v_and_b32_e32 v251, 0xffff0000, v246
	v_lshlrev_b32_e32 v246, 16, v247
	v_and_b32_e32 v247, 0xffff0000, v247
	v_pk_add_f32 v[170:171], v[170:171], v[244:245]
	v_pk_add_f32 v[168:169], v[168:169], v[248:249]
	v_pk_add_f32 v[244:245], v[162:163], v[246:247]
	v_pk_add_f32 v[246:247], v[160:161], v[250:251]
	v_cvt_pk_bf16_f32 v160, v168, v169
	v_cvt_pk_bf16_f32 v161, v170, v171
	s_nop 0
	v_cvt_pk_bf16_f32 v162, v246, v247
	v_cvt_pk_bf16_f32 v163, v244, v245
	global_store_dwordx4 v[228:229], v[160:163], off
	s_nop 1
	v_mul_f32_e32 v160, v169, v169
	v_mul_f32_e32 v161, v171, v171
	v_fmac_f32_e32 v160, v168, v168
	v_fmac_f32_e32 v161, v170, v170
	v_add_f32_e32 v160, v160, v161
	v_mul_f32_e32 v161, v247, v247
	v_fmac_f32_e32 v161, v246, v246
	v_add_f32_e32 v160, v161, v160
	v_mul_f32_e32 v161, v245, v245
	v_fmac_f32_e32 v161, v244, v244
	v_add_f32_e32 v196, v161, v160
	s_waitcnt vmcnt(15)
	v_lshlrev_b32_e32 v160, 16, v192
	v_and_b32_e32 v161, 0xffff0000, v192
	v_lshlrev_b32_e32 v162, 16, v193
	v_and_b32_e32 v163, 0xffff0000, v193
	v_lshlrev_b32_e32 v168, 16, v194
	v_and_b32_e32 v169, 0xffff0000, v194
	v_lshlrev_b32_e32 v170, 16, v195
	v_and_b32_e32 v171, 0xffff0000, v195
	v_pk_add_f32 v[138:139], v[138:139], v[162:163]
	v_pk_add_f32 v[136:137], v[136:137], v[160:161]
	v_pk_add_f32 v[162:163], v[128:129], v[168:169]
	v_cvt_pk_bf16_f32 v128, v136, v137
	v_cvt_pk_bf16_f32 v129, v138, v139
	v_pk_add_f32 v[160:161], v[130:131], v[170:171]
	v_cvt_pk_bf16_f32 v130, v162, v163
	s_nop 0
	v_cvt_pk_bf16_f32 v131, v160, v161
	global_store_dwordx4 v[228:229], v[128:131], off offset:256
	s_nop 1
	v_mul_f32_e32 v128, v137, v137
	v_mul_f32_e32 v129, v139, v139
	v_fmac_f32_e32 v128, v136, v136
	v_fmac_f32_e32 v129, v138, v138
	v_add_f32_e32 v128, v128, v129
	v_mul_f32_e32 v129, v163, v163
	v_fmac_f32_e32 v129, v162, v162
	v_add_f32_e32 v128, v129, v128
	v_mul_f32_e32 v129, v161, v161
	v_fmac_f32_e32 v129, v160, v160
	v_and_b32_e32 v130, 64, v236
	v_add_f32_e32 v128, v129, v128
	v_xor_b32_e32 v129, 16, v236
	v_add_u32_e32 v131, 64, v130
	v_cmp_lt_i32_e32 vcc, v129, v131
	v_add_f32_e32 v128, v196, v128
	s_nop 0
	v_cndmask_b32_e32 v129, v236, v129, vcc
	v_lshlrev_b32_e32 v130, 2, v129
	ds_bpermute_b32 v129, v130, v128
	s_waitcnt lgkmcnt(0)
	v_add_f32_e32 v136, v128, v129
	v_xor_b32_e32 v128, 32, v236
	v_cmp_lt_i32_e32 vcc, v128, v131
	s_nop 1
	v_cndmask_b32_e32 v128, v236, v128, vcc
	v_lshlrev_b32_e32 v131, 2, v128
	ds_bpermute_b32 v137, v131, v136
	v_lshl_add_u64 v[128:129], v[226:227], 3, s[52:53]
	s_and_saveexec_b64 s[26:27], s[40:41]
	s_cbranch_execz .LBB0_117
	s_waitcnt lgkmcnt(0)
	v_add_f32_e32 v136, v136, v137
	v_mul_f32_e32 v136, 0x4b800000, v136
	v_trunc_f32_e32 v136, v136
	v_mul_f32_e32 v137, 0x2f800000, v136
	v_floor_f32_e32 v137, v137
	v_fmac_f32_e32 v136, 0xcf800000, v137
	v_cvt_u32_f32_e32 v136, v136
	v_cvt_u32_f32_e32 v137, v137
	global_atomic_add_x2 v[128:129], v[136:137], off
; __device__ __forceinline__ unsigned long long f2ss(float v) { return (unsigned long long)(v * 16777216.0f); }
; __device__ __forceinline__ u32x4 pack8(f32x4 v0, f32x4 v1) { u32x4 w; w.x = cvt_pk_bf16(v0[0], v0[1]); w.y = cvt_pk_bf16(v0[2], v0[3]); w.z = cvt_pk_bf16(v1[0], v1[1]); w.w = cvt_pk_bf16(v1[2], v1[3]); return w; }
;     __device__ __forceinline__ void operator()(const f32x4 (&acc)[2][2][4][2], const Unit& u, int wr, int wc, int fr, int fq, const Pre&) const {
;     ...
;             for (int m = 0; m < 4; ++m) { const int row = row0 + ai * HALF + m * 16; const size_t off = (size_t)row * 1024 + col0; float sq = 0.f;
; #pragma unroll
;                 for (int bj = 0; bj < 2; ++bj) { const u32x4 bw = bwv[ai][m][bj];
;                     const f32x4 b0 = (f32x4){__uint_as_float(bw.x << 16), __uint_as_float(bw.x & 0xffff0000u), __uint_as_float(bw.y << 16), __uint_as_float(bw.y & 0xffff0000u)};
;                     const f32x4 b1 = (f32x4){__uint_as_float(bw.z << 16), __uint_as_float(bw.z & 0xffff0000u), __uint_as_float(bw.w << 16), __uint_as_float(bw.w & 0xffff0000u)};
;                     const f32x4 v0 = acc[ai][bj][m][0] + b0, v1 = acc[ai][bj][m][1] + b1;
;                     *(gu32x4*)(hb + off + bj * HALF) = pack8(v0, v1);
;                     sq += (v0[0] * v0[0] + v0[1] * v0[1]) + (v0[2] * v0[2] + v0[3] * v0[3]) + (v1[0] * v1[0] + v1[1] * v1[1]) + (v1[2] * v1[2] + v1[3] * v1[3]); }
;                 sq += __shfl_xor(sq, 16); sq += __shfl_xor(sq, 32); if (fq == 0) atomicAdd(ssn + row, f2ss(sq)); }
.LBB0_117:
	s_or_b64 exec, exec, s[26:27]
	s_waitcnt vmcnt(15)
	v_lshlrev_b32_e32 v136, 16, v188
	s_waitcnt lgkmcnt(0)
	v_and_b32_e32 v137, 0xffff0000, v188
	v_lshlrev_b32_e32 v138, 16, v189
	v_and_b32_e32 v139, 0xffff0000, v189
	v_lshlrev_b32_e32 v160, 16, v190
	v_and_b32_e32 v161, 0xffff0000, v190
	v_pk_add_f32 v[108:109], v[108:109], v[136:137]
	v_pk_add_f32 v[110:111], v[110:111], v[138:139]
	v_pk_add_f32 v[138:139], v[104:105], v[160:161]
	v_cvt_pk_bf16_f32 v104, v108, v109
	v_mul_f32_e32 v109, v109, v109
	v_fmac_f32_e32 v109, v108, v108
	v_mul_f32_e32 v108, v111, v111
	v_fmac_f32_e32 v108, v110, v110
	v_lshlrev_b32_e32 v162, 16, v191
	v_and_b32_e32 v163, 0xffff0000, v191
	v_add_f32_e32 v108, v109, v108
	v_mul_f32_e32 v109, v139, v139
	v_pk_add_f32 v[136:137], v[106:107], v[162:163]
	v_fmac_f32_e32 v109, v138, v138
	v_add_f32_e32 v108, v109, v108
	v_mul_f32_e32 v109, v137, v137
	v_fmac_f32_e32 v109, v136, v136
	v_cvt_pk_bf16_f32 v105, v110, v111
	v_add_f32_e32 v160, v109, v108
	s_waitcnt vmcnt(14)
	v_lshlrev_b32_e32 v108, 16, v184
	v_and_b32_e32 v109, 0xffff0000, v184
	v_lshlrev_b32_e32 v110, 16, v185
	v_and_b32_e32 v111, 0xffff0000, v185
	v_cvt_pk_bf16_f32 v106, v138, v139
	v_cvt_pk_bf16_f32 v107, v136, v137
	v_lshlrev_b32_e32 v136, 16, v186
	v_and_b32_e32 v137, 0xffff0000, v186
	v_pk_add_f32 v[102:103], v[102:103], v[110:111]
	v_pk_add_f32 v[100:101], v[100:101], v[108:109]
	v_pk_add_f32 v[110:111], v[96:97], v[136:137]
	v_mul_f32_e32 v96, v101, v101
	v_mul_f32_e32 v97, v103, v103
	v_fmac_f32_e32 v96, v100, v100
	v_fmac_f32_e32 v97, v102, v102
	v_lshlrev_b32_e32 v138, 16, v187
	v_and_b32_e32 v139, 0xffff0000, v187
	v_add_f32_e32 v96, v96, v97
	v_mul_f32_e32 v97, v111, v111
	v_pk_add_f32 v[108:109], v[98:99], v[138:139]
	v_fmac_f32_e32 v97, v110, v110
	v_add_f32_e32 v96, v97, v96
	v_mul_f32_e32 v97, v109, v109
	v_fmac_f32_e32 v97, v108, v108
	v_add_f32_e32 v96, v97, v96
	v_add_f32_e32 v99, v160, v96
	ds_bpermute_b32 v138, v130, v99
	v_lshl_add_u64 v[96:97], s[28:29], 0, v[224:225]
	v_lshl_add_u64 v[136:137], v[210:211], 1, v[96:97]
	global_store_dwordx4 v[136:137], v[104:107], off
	v_cvt_pk_bf16_f32 v98, v100, v101
	s_waitcnt lgkmcnt(0)
	v_add_f32_e32 v96, v99, v138
	ds_bpermute_b32 v97, v131, v96
	v_cvt_pk_bf16_f32 v99, v102, v103
	v_cvt_pk_bf16_f32 v100, v110, v111
	v_cvt_pk_bf16_f32 v101, v108, v109
	global_store_dwordx4 v[136:137], v[98:101], off offset:256
	s_and_saveexec_b64 s[26:27], s[40:41]
	s_cbranch_execz .LBB0_119
	s_waitcnt lgkmcnt(0)
	v_add_f32_e32 v96, v96, v97
	v_mul_f32_e32 v96, 0x4b800000, v96
	v_trunc_f32_e32 v96, v96
	v_mul_f32_e32 v97, 0x2f800000, v96
	v_floor_f32_e32 v97, v97
	v_fmac_f32_e32 v96, 0xcf800000, v97
	v_cvt_u32_f32_e32 v96, v96
	v_cvt_u32_f32_e32 v97, v97
	global_atomic_add_x2 v[128:129], v[96:97], off offset:128
.LBB0_119:
	s_or_b64 exec, exec, s[26:27]
	s_waitcnt vmcnt(15)
	v_lshlrev_b32_e32 v96, 16, v180
	s_waitcnt lgkmcnt(0)
	v_and_b32_e32 v97, 0xffff0000, v180
	v_lshlrev_b32_e32 v98, 16, v181
	v_and_b32_e32 v99, 0xffff0000, v181
	v_lshlrev_b32_e32 v100, 16, v182
	v_and_b32_e32 v101, 0xffff0000, v182
	v_pk_add_f32 v[92:93], v[92:93], v[96:97]
	v_pk_add_f32 v[94:95], v[94:95], v[98:99]
	v_pk_add_f32 v[98:99], v[88:89], v[100:101]
	v_cvt_pk_bf16_f32 v88, v92, v93
	v_mul_f32_e32 v93, v93, v93
	v_fmac_f32_e32 v93, v92, v92
	v_mul_f32_e32 v92, v95, v95
	v_fmac_f32_e32 v92, v94, v94
	v_lshlrev_b32_e32 v102, 16, v183
	v_and_b32_e32 v103, 0xffff0000, v183
	v_add_f32_e32 v92, v93, v92
	v_mul_f32_e32 v93, v99, v99
	v_pk_add_f32 v[96:97], v[90:91], v[102:103]
	v_fmac_f32_e32 v93, v98, v98
	v_add_f32_e32 v92, v93, v92
	v_mul_f32_e32 v93, v97, v97
	v_fmac_f32_e32 v93, v96, v96
	v_cvt_pk_bf16_f32 v89, v94, v95
	v_add_f32_e32 v100, v93, v92
	s_waitcnt vmcnt(14)
	v_lshlrev_b32_e32 v92, 16, v176
	v_and_b32_e32 v93, 0xffff0000, v176
	v_lshlrev_b32_e32 v94, 16, v177
	v_and_b32_e32 v95, 0xffff0000, v177
	v_cvt_pk_bf16_f32 v90, v98, v99
	v_cvt_pk_bf16_f32 v91, v96, v97
	v_lshlrev_b32_e32 v96, 16, v178
	v_and_b32_e32 v97, 0xffff0000, v178
	v_pk_add_f32 v[86:87], v[86:87], v[94:95]
	v_pk_add_f32 v[84:85], v[84:85], v[92:93]
	v_pk_add_f32 v[94:95], v[80:81], v[96:97]
	v_mul_f32_e32 v80, v85, v85
	v_mul_f32_e32 v81, v87, v87
	v_fmac_f32_e32 v80, v84, v84
	v_fmac_f32_e32 v81, v86, v86
	v_lshlrev_b32_e32 v98, 16, v179
	v_and_b32_e32 v99, 0xffff0000, v179
	v_add_f32_e32 v80, v80, v81
	v_mul_f32_e32 v81, v95, v95
	v_pk_add_f32 v[92:93], v[82:83], v[98:99]
	v_fmac_f32_e32 v81, v94, v94
	v_add_f32_e32 v80, v81, v80
	v_mul_f32_e32 v81, v93, v93
	v_fmac_f32_e32 v81, v92, v92
	v_add_f32_e32 v80, v81, v80
	v_add_f32_e32 v83, v100, v80
	ds_bpermute_b32 v98, v130, v83
	v_lshl_add_u64 v[80:81], s[28:29], 0, v[222:223]
	v_lshl_add_u64 v[96:97], v[210:211], 1, v[80:81]
	global_store_dwordx4 v[96:97], v[88:91], off
	v_cvt_pk_bf16_f32 v82, v84, v85
	s_waitcnt lgkmcnt(0)
	v_add_f32_e32 v80, v83, v98
	ds_bpermute_b32 v81, v131, v80
	v_cvt_pk_bf16_f32 v83, v86, v87
	v_cvt_pk_bf16_f32 v84, v94, v95
	v_cvt_pk_bf16_f32 v85, v92, v93
	global_store_dwordx4 v[96:97], v[82:85], off offset:256
	s_and_saveexec_b64 s[26:27], s[40:41]
	s_cbranch_execz .LBB0_121
	s_waitcnt lgkmcnt(0)
	v_add_f32_e32 v80, v80, v81
	v_mul_f32_e32 v80, 0x4b800000, v80
	v_trunc_f32_e32 v80, v80
	v_mul_f32_e32 v81, 0x2f800000, v80
	v_floor_f32_e32 v81, v81
	v_fmac_f32_e32 v80, 0xcf800000, v81
	v_cvt_u32_f32_e32 v80, v80
	v_cvt_u32_f32_e32 v81, v81
	global_atomic_add_x2 v[128:129], v[80:81], off offset:256
; __device__ __forceinline__ unsigned long long f2ss(float v) { return (unsigned long long)(v * 16777216.0f); }
; __device__ __forceinline__ u32x4 pack8(f32x4 v0, f32x4 v1) { u32x4 w; w.x = cvt_pk_bf16(v0[0], v0[1]); w.y = cvt_pk_bf16(v0[2], v0[3]); w.z = cvt_pk_bf16(v1[0], v1[1]); w.w = cvt_pk_bf16(v1[2], v1[3]); return w; }
;     __device__ __forceinline__ void operator()(const f32x4 (&acc)[2][2][4][2], const Unit& u, int wr, int wc, int fr, int fq, const Pre&) const {
;     ...
;             for (int m = 0; m < 4; ++m) { const int row = row0 + ai * HALF + m * 16; const size_t off = (size_t)row * 1024 + col0; float sq = 0.f;
; #pragma unroll
;                 for (int bj = 0; bj < 2; ++bj) { const u32x4 bw = bwv[ai][m][bj];
;                     const f32x4 b0 = (f32x4){__uint_as_float(bw.x << 16), __uint_as_float(bw.x & 0xffff0000u), __uint_as_float(bw.y << 16), __uint_as_float(bw.y & 0xffff0000u)};
;                     const f32x4 b1 = (f32x4){__uint_as_float(bw.z << 16), __uint_as_float(bw.z & 0xffff0000u), __uint_as_float(bw.w << 16), __uint_as_float(bw.w & 0xffff0000u)};
;                     const f32x4 v0 = acc[ai][bj][m][0] + b0, v1 = acc[ai][bj][m][1] + b1;
;                     *(gu32x4*)(hb + off + bj * HALF) = pack8(v0, v1);
;                     sq += (v0[0] * v0[0] + v0[1] * v0[1]) + (v0[2] * v0[2] + v0[3] * v0[3]) + (v1[0] * v1[0] + v1[1] * v1[1]) + (v1[2] * v1[2] + v1[3] * v1[3]); }
;                 sq += __shfl_xor(sq, 16); sq += __shfl_xor(sq, 32); if (fq == 0) atomicAdd(ssn + row, f2ss(sq)); }
.LBB0_121:
	s_or_b64 exec, exec, s[26:27]
	s_waitcnt vmcnt(15)
	v_lshlrev_b32_e32 v80, 16, v172
	s_waitcnt lgkmcnt(0)
	v_and_b32_e32 v81, 0xffff0000, v172
	v_lshlrev_b32_e32 v82, 16, v173
	v_and_b32_e32 v83, 0xffff0000, v173
	v_lshlrev_b32_e32 v84, 16, v174
	v_and_b32_e32 v85, 0xffff0000, v174
	v_pk_add_f32 v[76:77], v[76:77], v[80:81]
	v_pk_add_f32 v[78:79], v[78:79], v[82:83]
	v_pk_add_f32 v[82:83], v[72:73], v[84:85]
	v_cvt_pk_bf16_f32 v72, v76, v77
	v_mul_f32_e32 v77, v77, v77
	v_fmac_f32_e32 v77, v76, v76
	v_mul_f32_e32 v76, v79, v79
	v_fmac_f32_e32 v76, v78, v78
	v_lshlrev_b32_e32 v86, 16, v175
	v_and_b32_e32 v87, 0xffff0000, v175
	v_add_f32_e32 v76, v77, v76
	v_mul_f32_e32 v77, v83, v83
	v_pk_add_f32 v[80:81], v[74:75], v[86:87]
	v_fmac_f32_e32 v77, v82, v82
	v_add_f32_e32 v76, v77, v76
	v_mul_f32_e32 v77, v81, v81
	v_fmac_f32_e32 v77, v80, v80
	v_cvt_pk_bf16_f32 v73, v78, v79
	v_add_f32_e32 v84, v77, v76
	s_waitcnt vmcnt(14)
	v_lshlrev_b32_e32 v76, 16, v164
	v_and_b32_e32 v77, 0xffff0000, v164
	v_lshlrev_b32_e32 v78, 16, v165
	v_and_b32_e32 v79, 0xffff0000, v165
	v_cvt_pk_bf16_f32 v74, v82, v83
	v_cvt_pk_bf16_f32 v75, v80, v81
	v_lshlrev_b32_e32 v80, 16, v166
	v_and_b32_e32 v81, 0xffff0000, v166
	v_pk_add_f32 v[70:71], v[70:71], v[78:79]
	v_pk_add_f32 v[68:69], v[68:69], v[76:77]
	v_pk_add_f32 v[78:79], v[64:65], v[80:81]
	v_mul_f32_e32 v64, v69, v69
	v_mul_f32_e32 v65, v71, v71
	v_fmac_f32_e32 v64, v68, v68
	v_fmac_f32_e32 v65, v70, v70
	v_lshlrev_b32_e32 v82, 16, v167
	v_and_b32_e32 v83, 0xffff0000, v167
	v_add_f32_e32 v64, v64, v65
	v_mul_f32_e32 v65, v79, v79
	v_pk_add_f32 v[76:77], v[66:67], v[82:83]
	v_fmac_f32_e32 v65, v78, v78
	v_add_f32_e32 v64, v65, v64
	v_mul_f32_e32 v65, v77, v77
	v_fmac_f32_e32 v65, v76, v76
	v_add_f32_e32 v64, v65, v64
	v_add_f32_e32 v67, v84, v64
	ds_bpermute_b32 v82, v130, v67
	v_lshl_add_u64 v[64:65], s[28:29], 0, v[220:221]
	v_lshl_add_u64 v[80:81], v[210:211], 1, v[64:65]
	global_store_dwordx4 v[80:81], v[72:75], off
	v_cvt_pk_bf16_f32 v66, v68, v69
	s_waitcnt lgkmcnt(0)
	v_add_f32_e32 v64, v67, v82
	ds_bpermute_b32 v65, v131, v64
	v_cvt_pk_bf16_f32 v67, v70, v71
	v_cvt_pk_bf16_f32 v68, v78, v79
	v_cvt_pk_bf16_f32 v69, v76, v77
	global_store_dwordx4 v[80:81], v[66:69], off offset:256
	s_and_saveexec_b64 s[26:27], s[40:41]
	s_cbranch_execz .LBB0_123
	s_waitcnt lgkmcnt(0)
	v_add_f32_e32 v64, v64, v65
	v_mul_f32_e32 v64, 0x4b800000, v64
	v_trunc_f32_e32 v64, v64
	v_mul_f32_e32 v65, 0x2f800000, v64
	v_floor_f32_e32 v65, v65
	v_fmac_f32_e32 v64, 0xcf800000, v65
	v_cvt_u32_f32_e32 v64, v64
	v_cvt_u32_f32_e32 v65, v65
	global_atomic_add_x2 v[128:129], v[64:65], off offset:384
.LBB0_123:
	s_or_b64 exec, exec, s[26:27]
	s_waitcnt vmcnt(15)
	v_lshlrev_b32_e32 v64, 16, v156
	s_waitcnt lgkmcnt(0)
	v_and_b32_e32 v65, 0xffff0000, v156
	v_lshlrev_b32_e32 v66, 16, v157
	v_and_b32_e32 v67, 0xffff0000, v157
	v_lshlrev_b32_e32 v68, 16, v158
	v_and_b32_e32 v69, 0xffff0000, v158
	v_pk_add_f32 v[60:61], v[60:61], v[64:65]
	v_pk_add_f32 v[62:63], v[62:63], v[66:67]
	v_pk_add_f32 v[66:67], v[56:57], v[68:69]
	v_cvt_pk_bf16_f32 v56, v60, v61
	v_mul_f32_e32 v61, v61, v61
	v_fmac_f32_e32 v61, v60, v60
	v_mul_f32_e32 v60, v63, v63
	v_fmac_f32_e32 v60, v62, v62
	v_lshlrev_b32_e32 v70, 16, v159
	v_and_b32_e32 v71, 0xffff0000, v159
	v_add_f32_e32 v60, v61, v60
	v_mul_f32_e32 v61, v67, v67
	v_pk_add_f32 v[64:65], v[58:59], v[70:71]
	v_fmac_f32_e32 v61, v66, v66
	v_add_f32_e32 v60, v61, v60
	v_mul_f32_e32 v61, v65, v65
	v_fmac_f32_e32 v61, v64, v64
	v_cvt_pk_bf16_f32 v57, v62, v63
	v_add_f32_e32 v68, v61, v60
	s_waitcnt vmcnt(14)
	v_lshlrev_b32_e32 v60, 16, v152
	v_and_b32_e32 v61, 0xffff0000, v152
	v_lshlrev_b32_e32 v62, 16, v153
	v_and_b32_e32 v63, 0xffff0000, v153
	v_cvt_pk_bf16_f32 v58, v66, v67
	v_cvt_pk_bf16_f32 v59, v64, v65
	v_lshlrev_b32_e32 v64, 16, v154
	v_and_b32_e32 v65, 0xffff0000, v154
	v_pk_add_f32 v[54:55], v[54:55], v[62:63]
	v_pk_add_f32 v[52:53], v[52:53], v[60:61]
	v_pk_add_f32 v[62:63], v[48:49], v[64:65]
	v_mul_f32_e32 v48, v53, v53
	v_mul_f32_e32 v49, v55, v55
	v_fmac_f32_e32 v48, v52, v52
	v_fmac_f32_e32 v49, v54, v54
	v_lshlrev_b32_e32 v66, 16, v155
	v_and_b32_e32 v67, 0xffff0000, v155
	v_add_f32_e32 v48, v48, v49
	v_mul_f32_e32 v49, v63, v63
	v_pk_add_f32 v[60:61], v[50:51], v[66:67]
	v_fmac_f32_e32 v49, v62, v62
	v_add_f32_e32 v48, v49, v48
	v_mul_f32_e32 v49, v61, v61
	v_fmac_f32_e32 v49, v60, v60
	v_add_f32_e32 v48, v49, v48
	v_add_f32_e32 v51, v68, v48
	ds_bpermute_b32 v66, v130, v51
	v_lshl_add_u64 v[48:49], s[28:29], 0, v[218:219]
	v_lshl_add_u64 v[64:65], v[210:211], 1, v[48:49]
	global_store_dwordx4 v[64:65], v[56:59], off
	v_cvt_pk_bf16_f32 v50, v52, v53
	s_waitcnt lgkmcnt(0)
	v_add_f32_e32 v48, v51, v66
	ds_bpermute_b32 v49, v131, v48
	v_cvt_pk_bf16_f32 v51, v54, v55
	v_cvt_pk_bf16_f32 v52, v62, v63
	v_cvt_pk_bf16_f32 v53, v60, v61
	global_store_dwordx4 v[64:65], v[50:53], off offset:256
	s_and_saveexec_b64 s[26:27], s[40:41]
	s_cbranch_execz .LBB0_125
	s_waitcnt lgkmcnt(0)
	v_add_f32_e32 v48, v48, v49
	v_mul_f32_e32 v48, 0x4b800000, v48
	v_trunc_f32_e32 v48, v48
	v_mul_f32_e32 v49, 0x2f800000, v48
	v_floor_f32_e32 v49, v49
	v_fmac_f32_e32 v48, 0xcf800000, v49
	v_cvt_u32_f32_e32 v48, v48
	v_cvt_u32_f32_e32 v49, v49
	global_atomic_add_x2 v[128:129], v[48:49], off offset:1024
; __device__ __forceinline__ unsigned long long f2ss(float v) { return (unsigned long long)(v * 16777216.0f); }
; __device__ __forceinline__ u32x4 pack8(f32x4 v0, f32x4 v1) { u32x4 w; w.x = cvt_pk_bf16(v0[0], v0[1]); w.y = cvt_pk_bf16(v0[2], v0[3]); w.z = cvt_pk_bf16(v1[0], v1[1]); w.w = cvt_pk_bf16(v1[2], v1[3]); return w; }
;     __device__ __forceinline__ void operator()(const f32x4 (&acc)[2][2][4][2], const Unit& u, int wr, int wc, int fr, int fq, const Pre&) const {
;     ...
;             for (int m = 0; m < 4; ++m) { const int row = row0 + ai * HALF + m * 16; const size_t off = (size_t)row * 1024 + col0; float sq = 0.f;
; #pragma unroll
;                 for (int bj = 0; bj < 2; ++bj) { const u32x4 bw = bwv[ai][m][bj];
;                     const f32x4 b0 = (f32x4){__uint_as_float(bw.x << 16), __uint_as_float(bw.x & 0xffff0000u), __uint_as_float(bw.y << 16), __uint_as_float(bw.y & 0xffff0000u)};
;                     const f32x4 b1 = (f32x4){__uint_as_float(bw.z << 16), __uint_as_float(bw.z & 0xffff0000u), __uint_as_float(bw.w << 16), __uint_as_float(bw.w & 0xffff0000u)};
;                     const f32x4 v0 = acc[ai][bj][m][0] + b0, v1 = acc[ai][bj][m][1] + b1;
;                     *(gu32x4*)(hb + off + bj * HALF) = pack8(v0, v1);
;                     sq += (v0[0] * v0[0] + v0[1] * v0[1]) + (v0[2] * v0[2] + v0[3] * v0[3]) + (v1[0] * v1[0] + v1[1] * v1[1]) + (v1[2] * v1[2] + v1[3] * v1[3]); }
;                 sq += __shfl_xor(sq, 16); sq += __shfl_xor(sq, 32); if (fq == 0) atomicAdd(ssn + row, f2ss(sq)); }
.LBB0_125:
	s_or_b64 exec, exec, s[26:27]
	s_waitcnt vmcnt(15)
	v_lshlrev_b32_e32 v48, 16, v140
	s_waitcnt lgkmcnt(0)
	v_and_b32_e32 v49, 0xffff0000, v140
	v_lshlrev_b32_e32 v50, 16, v141
	v_and_b32_e32 v51, 0xffff0000, v141
	v_lshlrev_b32_e32 v52, 16, v142
	v_and_b32_e32 v53, 0xffff0000, v142
	v_pk_add_f32 v[44:45], v[44:45], v[48:49]
	v_pk_add_f32 v[46:47], v[46:47], v[50:51]
	v_pk_add_f32 v[50:51], v[40:41], v[52:53]
	v_cvt_pk_bf16_f32 v40, v44, v45
	v_mul_f32_e32 v45, v45, v45
	v_fmac_f32_e32 v45, v44, v44
	v_mul_f32_e32 v44, v47, v47
	v_fmac_f32_e32 v44, v46, v46
	v_lshlrev_b32_e32 v54, 16, v143
	v_and_b32_e32 v55, 0xffff0000, v143
	v_add_f32_e32 v44, v45, v44
	v_mul_f32_e32 v45, v51, v51
	v_pk_add_f32 v[48:49], v[42:43], v[54:55]
	v_fmac_f32_e32 v45, v50, v50
	v_add_f32_e32 v44, v45, v44
	v_mul_f32_e32 v45, v49, v49
	v_fmac_f32_e32 v45, v48, v48
	v_cvt_pk_bf16_f32 v41, v46, v47
	v_add_f32_e32 v52, v45, v44
	s_waitcnt vmcnt(14)
	v_lshlrev_b32_e32 v44, 16, v132
	v_and_b32_e32 v45, 0xffff0000, v132
	v_lshlrev_b32_e32 v46, 16, v133
	v_and_b32_e32 v47, 0xffff0000, v133
	v_cvt_pk_bf16_f32 v42, v50, v51
	v_cvt_pk_bf16_f32 v43, v48, v49
	v_lshlrev_b32_e32 v48, 16, v134
	v_and_b32_e32 v49, 0xffff0000, v134
	v_pk_add_f32 v[38:39], v[38:39], v[46:47]
	v_pk_add_f32 v[36:37], v[36:37], v[44:45]
	v_pk_add_f32 v[46:47], v[32:33], v[48:49]
	v_mul_f32_e32 v32, v37, v37
	v_mul_f32_e32 v33, v39, v39
	v_fmac_f32_e32 v32, v36, v36
	v_fmac_f32_e32 v33, v38, v38
	v_lshlrev_b32_e32 v50, 16, v135
	v_and_b32_e32 v51, 0xffff0000, v135
	v_add_f32_e32 v32, v32, v33
	v_mul_f32_e32 v33, v47, v47
	v_pk_add_f32 v[44:45], v[34:35], v[50:51]
	v_fmac_f32_e32 v33, v46, v46
	v_add_f32_e32 v32, v33, v32
	v_mul_f32_e32 v33, v45, v45
	v_fmac_f32_e32 v33, v44, v44
	v_add_f32_e32 v32, v33, v32
	v_add_f32_e32 v35, v52, v32
	ds_bpermute_b32 v50, v130, v35
	v_lshl_add_u64 v[32:33], s[28:29], 0, v[216:217]
	v_lshl_add_u64 v[48:49], v[210:211], 1, v[32:33]
	global_store_dwordx4 v[48:49], v[40:43], off
	v_cvt_pk_bf16_f32 v34, v36, v37
	s_waitcnt lgkmcnt(0)
	v_add_f32_e32 v32, v35, v50
	ds_bpermute_b32 v33, v131, v32
	v_cvt_pk_bf16_f32 v35, v38, v39
	v_cvt_pk_bf16_f32 v36, v46, v47
	v_cvt_pk_bf16_f32 v37, v44, v45
	global_store_dwordx4 v[48:49], v[34:37], off offset:256
	s_and_saveexec_b64 s[26:27], s[40:41]
	s_cbranch_execz .LBB0_127
	s_waitcnt lgkmcnt(0)
	v_add_f32_e32 v32, v32, v33
	v_mul_f32_e32 v32, 0x4b800000, v32
	v_trunc_f32_e32 v32, v32
	v_mul_f32_e32 v33, 0x2f800000, v32
	v_floor_f32_e32 v33, v33
	v_fmac_f32_e32 v32, 0xcf800000, v33
	v_cvt_u32_f32_e32 v32, v32
	v_cvt_u32_f32_e32 v33, v33
	global_atomic_add_x2 v[128:129], v[32:33], off offset:1152
; __device__ __forceinline__ unsigned long long f2ss(float v) { return (unsigned long long)(v * 16777216.0f); }
; __device__ __forceinline__ u32x4 pack8(f32x4 v0, f32x4 v1) { u32x4 w; w.x = cvt_pk_bf16(v0[0], v0[1]); w.y = cvt_pk_bf16(v0[2], v0[3]); w.z = cvt_pk_bf16(v1[0], v1[1]); w.w = cvt_pk_bf16(v1[2], v1[3]); return w; }
;     __device__ __forceinline__ void operator()(const f32x4 (&acc)[2][2][4][2], const Unit& u, int wr, int wc, int fr, int fq, const Pre&) const {
;     ...
;             for (int m = 0; m < 4; ++m) { const int row = row0 + ai * HALF + m * 16; const size_t off = (size_t)row * 1024 + col0; float sq = 0.f;
; #pragma unroll
;                 for (int bj = 0; bj < 2; ++bj) { const u32x4 bw = bwv[ai][m][bj];
;                     const f32x4 b0 = (f32x4){__uint_as_float(bw.x << 16), __uint_as_float(bw.x & 0xffff0000u), __uint_as_float(bw.y << 16), __uint_as_float(bw.y & 0xffff0000u)};
;                     const f32x4 b1 = (f32x4){__uint_as_float(bw.z << 16), __uint_as_float(bw.z & 0xffff0000u), __uint_as_float(bw.w << 16), __uint_as_float(bw.w & 0xffff0000u)};
;                     const f32x4 v0 = acc[ai][bj][m][0] + b0, v1 = acc[ai][bj][m][1] + b1;
;                     *(gu32x4*)(hb + off + bj * HALF) = pack8(v0, v1);
;                     sq += (v0[0] * v0[0] + v0[1] * v0[1]) + (v0[2] * v0[2] + v0[3] * v0[3]) + (v1[0] * v1[0] + v1[1] * v1[1]) + (v1[2] * v1[2] + v1[3] * v1[3]); }
;                 sq += __shfl_xor(sq, 16); sq += __shfl_xor(sq, 32); if (fq == 0) atomicAdd(ssn + row, f2ss(sq)); }
.LBB0_127:
	s_or_b64 exec, exec, s[26:27]
	s_waitcnt vmcnt(15)
	v_lshlrev_b32_e32 v32, 16, v124
	s_waitcnt lgkmcnt(0)
	v_and_b32_e32 v33, 0xffff0000, v124
	v_lshlrev_b32_e32 v34, 16, v125
	v_and_b32_e32 v35, 0xffff0000, v125
	v_lshlrev_b32_e32 v36, 16, v126
	v_and_b32_e32 v37, 0xffff0000, v126
	v_pk_add_f32 v[28:29], v[28:29], v[32:33]
	v_pk_add_f32 v[30:31], v[30:31], v[34:35]
	v_pk_add_f32 v[34:35], v[24:25], v[36:37]
	v_cvt_pk_bf16_f32 v24, v28, v29
	v_mul_f32_e32 v29, v29, v29
	v_fmac_f32_e32 v29, v28, v28
	v_mul_f32_e32 v28, v31, v31
	v_fmac_f32_e32 v28, v30, v30
	v_lshlrev_b32_e32 v38, 16, v127
	v_and_b32_e32 v39, 0xffff0000, v127
	v_add_f32_e32 v28, v29, v28
	v_mul_f32_e32 v29, v35, v35
	v_pk_add_f32 v[32:33], v[26:27], v[38:39]
	v_fmac_f32_e32 v29, v34, v34
	v_add_f32_e32 v28, v29, v28
	v_mul_f32_e32 v29, v33, v33
	v_fmac_f32_e32 v29, v32, v32
	v_cvt_pk_bf16_f32 v25, v30, v31
	v_add_f32_e32 v36, v29, v28
	s_waitcnt vmcnt(14)
	v_lshlrev_b32_e32 v28, 16, v116
	v_and_b32_e32 v29, 0xffff0000, v116
	v_lshlrev_b32_e32 v30, 16, v117
	v_and_b32_e32 v31, 0xffff0000, v117
	v_cvt_pk_bf16_f32 v26, v34, v35
	v_cvt_pk_bf16_f32 v27, v32, v33
	v_lshlrev_b32_e32 v32, 16, v118
	v_and_b32_e32 v33, 0xffff0000, v118
	v_pk_add_f32 v[22:23], v[22:23], v[30:31]
	v_pk_add_f32 v[20:21], v[20:21], v[28:29]
	v_pk_add_f32 v[30:31], v[16:17], v[32:33]
	v_mul_f32_e32 v16, v21, v21
	v_mul_f32_e32 v17, v23, v23
	v_fmac_f32_e32 v16, v20, v20
	v_fmac_f32_e32 v17, v22, v22
	v_lshlrev_b32_e32 v34, 16, v119
	v_and_b32_e32 v35, 0xffff0000, v119
	v_add_f32_e32 v16, v16, v17
	v_mul_f32_e32 v17, v31, v31
	v_pk_add_f32 v[28:29], v[18:19], v[34:35]
	v_fmac_f32_e32 v17, v30, v30
	v_add_f32_e32 v16, v17, v16
	v_mul_f32_e32 v17, v29, v29
	v_fmac_f32_e32 v17, v28, v28
	v_add_f32_e32 v16, v17, v16
	v_add_f32_e32 v19, v36, v16
	ds_bpermute_b32 v34, v130, v19
	v_lshl_add_u64 v[16:17], s[28:29], 0, v[214:215]
	v_lshl_add_u64 v[32:33], v[210:211], 1, v[16:17]
	global_store_dwordx4 v[32:33], v[24:27], off
	v_cvt_pk_bf16_f32 v18, v20, v21
	s_waitcnt lgkmcnt(0)
	v_add_f32_e32 v16, v19, v34
	ds_bpermute_b32 v17, v131, v16
	v_cvt_pk_bf16_f32 v19, v22, v23
	v_cvt_pk_bf16_f32 v20, v30, v31
	v_cvt_pk_bf16_f32 v21, v28, v29
	global_store_dwordx4 v[32:33], v[18:21], off offset:256
	s_and_saveexec_b64 s[26:27], s[40:41]
	s_cbranch_execz .LBB0_129
	s_waitcnt lgkmcnt(0)
	v_add_f32_e32 v16, v16, v17
	v_mul_f32_e32 v16, 0x4b800000, v16
	v_trunc_f32_e32 v16, v16
	v_mul_f32_e32 v17, 0x2f800000, v16
	v_floor_f32_e32 v17, v17
	v_fmac_f32_e32 v16, 0xcf800000, v17
	v_cvt_u32_f32_e32 v16, v16
	v_cvt_u32_f32_e32 v17, v17
	global_atomic_add_x2 v[128:129], v[16:17], off offset:1280
.LBB0_129:
	s_or_b64 exec, exec, s[26:27]
	s_waitcnt vmcnt(15)
	v_lshlrev_b32_e32 v16, 16, v120
	s_waitcnt lgkmcnt(0)
	v_and_b32_e32 v17, 0xffff0000, v120
	v_lshlrev_b32_e32 v18, 16, v121
	v_and_b32_e32 v19, 0xffff0000, v121
	v_lshlrev_b32_e32 v20, 16, v122
	v_and_b32_e32 v21, 0xffff0000, v122
	v_pk_add_f32 v[12:13], v[12:13], v[16:17]
	v_pk_add_f32 v[14:15], v[14:15], v[18:19]
	v_pk_add_f32 v[18:19], v[8:9], v[20:21]
	v_cvt_pk_bf16_f32 v8, v12, v13
	v_mul_f32_e32 v13, v13, v13
	v_fmac_f32_e32 v13, v12, v12
	v_mul_f32_e32 v12, v15, v15
	v_fmac_f32_e32 v12, v14, v14
	v_lshlrev_b32_e32 v22, 16, v123
	v_and_b32_e32 v23, 0xffff0000, v123
	v_add_f32_e32 v12, v13, v12
	v_mul_f32_e32 v13, v19, v19
	v_pk_add_f32 v[16:17], v[10:11], v[22:23]
	v_fmac_f32_e32 v13, v18, v18
	v_add_f32_e32 v12, v13, v12
	v_mul_f32_e32 v13, v17, v17
	v_fmac_f32_e32 v13, v16, v16
	v_cvt_pk_bf16_f32 v9, v14, v15
	v_add_f32_e32 v20, v13, v12
	s_waitcnt vmcnt(14)
	v_lshlrev_b32_e32 v12, 16, v112
	v_and_b32_e32 v13, 0xffff0000, v112
	v_lshlrev_b32_e32 v14, 16, v113
	v_and_b32_e32 v15, 0xffff0000, v113
	v_cvt_pk_bf16_f32 v10, v18, v19
	v_cvt_pk_bf16_f32 v11, v16, v17
	v_lshlrev_b32_e32 v16, 16, v114
	v_and_b32_e32 v17, 0xffff0000, v114
	v_pk_add_f32 v[6:7], v[6:7], v[14:15]
	v_pk_add_f32 v[4:5], v[4:5], v[12:13]
	v_pk_add_f32 v[14:15], v[0:1], v[16:17]
	v_mul_f32_e32 v0, v5, v5
	v_mul_f32_e32 v1, v7, v7
	v_fmac_f32_e32 v0, v4, v4
	v_fmac_f32_e32 v1, v6, v6
	v_lshlrev_b32_e32 v18, 16, v115
	v_and_b32_e32 v19, 0xffff0000, v115
	v_add_f32_e32 v0, v0, v1
	v_mul_f32_e32 v1, v15, v15
	v_pk_add_f32 v[12:13], v[2:3], v[18:19]
	v_fmac_f32_e32 v1, v14, v14
	v_add_f32_e32 v0, v1, v0
	v_mul_f32_e32 v1, v13, v13
	v_fmac_f32_e32 v1, v12, v12
	v_add_f32_e32 v0, v1, v0
	v_add_f32_e32 v3, v20, v0
	ds_bpermute_b32 v18, v130, v3
	v_lshl_add_u64 v[0:1], s[28:29], 0, v[212:213]
	v_lshl_add_u64 v[16:17], v[210:211], 1, v[0:1]
	global_store_dwordx4 v[16:17], v[8:11], off
	v_cvt_pk_bf16_f32 v2, v4, v5
	s_waitcnt lgkmcnt(0)
	v_add_f32_e32 v0, v3, v18
	ds_bpermute_b32 v1, v131, v0
	v_cvt_pk_bf16_f32 v3, v6, v7
	v_cvt_pk_bf16_f32 v4, v14, v15
	v_cvt_pk_bf16_f32 v5, v12, v13
	global_store_dwordx4 v[16:17], v[2:5], off offset:256
	s_and_saveexec_b64 s[26:27], s[40:41]
	s_cbranch_execz .LBB0_131
	s_waitcnt lgkmcnt(0)
	v_add_f32_e32 v0, v0, v1
	v_mul_f32_e32 v0, 0x4b800000, v0
	v_trunc_f32_e32 v0, v0
	v_mul_f32_e32 v1, 0x2f800000, v0
	v_floor_f32_e32 v1, v1
	v_fmac_f32_e32 v0, 0xcf800000, v1
	v_cvt_u32_f32_e32 v0, v0
	v_cvt_u32_f32_e32 v1, v1
	global_atomic_add_x2 v[128:129], v[0:1], off offset:1408

; __device__ __forceinline__ unsigned long long f2ss(float v) { return (unsigned long long)(v * 16777216.0f); }
; __device__ __forceinline__ u32x4 pack8(f32x4 v0, f32x4 v1) { u32x4 w; w.x = cvt_pk_bf16(v0[0], v0[1]); w.y = cvt_pk_bf16(v0[2], v0[3]); w.z = cvt_pk_bf16(v1[0], v1[1]); w.w = cvt_pk_bf16(v1[2], v1[3]); return w; }
;     __device__ __forceinline__ void operator()(const f32x4 (&acc)[2][2][4][2], const Unit& u, int wr, int wc, int fr, int fq, const Pre&) const {
;         const int row0 = u.pm * BM + wr * 64 + fr, col0 = u.pn * BM + wc * 32 + 8 * fq;
;         typedef __attribute__((address_space(1))) u32x4 gu32x4;
;         u32x4 bwv[2][4][2];
; #pragma unroll
;         for (int ai = 0; ai < 2; ++ai)
; #pragma unroll
;             for (int m = 0; m < 4; ++m)
; #pragma unroll
;                 for (int bj = 0; bj < 2; ++bj) bwv[ai][m][bj] = *(const gu32x4*)(hb + (size_t)(row0 + ai * HALF + m * 16) * 1024 + col0 + bj * HALF);
; #pragma unroll
;         for (int ai = 0; ai < 2; ++ai)
; #pragma unroll
;             for (int m = 0; m < 4; ++m) { const int row = row0 + ai * HALF + m * 16; const size_t off = (size_t)row * 1024 + col0; float sq = 0.f;
; #pragma unroll
;                 for (int bj = 0; bj < 2; ++bj) { const u32x4 bw = bwv[ai][m][bj];
;                     const f32x4 b0 = (f32x4){__uint_as_float(bw.x << 16), __uint_as_float(bw.x & 0xffff0000u), __uint_as_float(bw.y << 16), __uint_as_float(bw.y & 0xffff0000u)};
;                     const f32x4 b1 = (f32x4){__uint_as_float(bw.z << 16), __uint_as_float(bw.z & 0xffff0000u), __uint_as_float(bw.w << 16), __uint_as_float(bw.w & 0xffff0000u)};
;                     const f32x4 v0 = acc[ai][bj][m][0] + b0, v1 = acc[ai][bj][m][1] + b1;
;                     *(gu32x4*)(hb + off + bj * HALF) = pack8(v0, v1);
;                     sq += (v0[0] * v0[0] + v0[1] * v0[1]) + (v0[2] * v0[2] + v0[3] * v0[3]) + (v1[0] * v1[0] + v1[1] * v1[1]) + (v1[2] * v1[2] + v1[3] * v1[3]); }
;                 sq += __shfl_xor(sq, 16); sq += __shfl_xor(sq, 32); if (fq == 0) atomicAdd(ssn + row, f2ss(sq)); }
.LBB0_177:
	v_lshl_or_b32 v210, s36, 8, v241
	v_lshl_add_u32 v226, s4, 8, v145
	v_ashrrev_i32_e32 v211, 31, v210
	v_lshlrev_b64 v[228:229], 1, v[210:211]
	v_ashrrev_i32_e32 v227, 31, v226
	v_lshl_add_u64 v[112:113], s[28:29], 0, v[228:229]
	v_lshlrev_b64 v[230:231], 11, v[226:227]
	v_lshl_add_u64 v[114:115], v[112:113], 0, v[230:231]
	global_load_dwordx4 v[244:247], v[114:115], off
	global_load_dwordx4 v[192:195], v[114:115], off offset:256
	v_or_b32_e32 v114, 16, v226
	v_ashrrev_i32_e32 v115, 31, v114
	v_lshlrev_b64 v[224:225], 11, v[114:115]
	v_lshl_add_u64 v[114:115], v[112:113], 0, v[224:225]
	global_load_dwordx4 v[188:191], v[114:115], off
	global_load_dwordx4 v[184:187], v[114:115], off offset:256
	v_or_b32_e32 v114, 32, v226
	v_ashrrev_i32_e32 v115, 31, v114
	v_lshlrev_b64 v[222:223], 11, v[114:115]
	v_lshl_add_u64 v[114:115], v[112:113], 0, v[222:223]
	global_load_dwordx4 v[180:183], v[114:115], off
	global_load_dwordx4 v[176:179], v[114:115], off offset:256
	v_or_b32_e32 v114, 48, v226
	v_ashrrev_i32_e32 v115, 31, v114
	s_mov_b64 s[4:5], 0x40000
	v_lshlrev_b64 v[220:221], 11, v[114:115]
	v_lshl_add_u64 v[218:219], v[230:231], 0, s[4:5]
	s_mov_b64 s[4:5], 0x48000
	v_lshl_add_u64 v[114:115], v[112:113], 0, v[220:221]
	v_lshl_add_u64 v[216:217], v[230:231], 0, s[4:5]
	s_mov_b64 s[4:5], 0x50000
	global_load_dwordx4 v[172:175], v[114:115], off
	global_load_dwordx4 v[164:167], v[114:115], off offset:256
	v_lshl_add_u64 v[114:115], v[112:113], 0, v[218:219]
	v_lshl_add_u64 v[214:215], v[230:231], 0, s[4:5]
	s_mov_b64 s[4:5], 0x58000
	global_load_dwordx4 v[156:159], v[114:115], off
	global_load_dwordx4 v[152:155], v[114:115], off offset:256
	v_lshl_add_u64 v[114:115], v[112:113], 0, v[216:217]
	v_lshl_add_u64 v[212:213], v[230:231], 0, s[4:5]
	global_load_dwordx4 v[140:143], v[114:115], off
	global_load_dwordx4 v[136:139], v[114:115], off offset:256
	v_lshl_add_u64 v[114:115], v[112:113], 0, v[214:215]
	v_lshl_add_u64 v[112:113], v[112:113], 0, v[212:213]
	global_load_dwordx4 v[124:127], v[114:115], off
	global_load_dwordx4 v[116:119], v[114:115], off offset:256
	global_load_dwordx4 v[120:123], v[112:113], off
	s_nop 0
	global_load_dwordx4 v[112:115], v[112:113], off offset:256
	v_lshl_add_u64 v[230:231], s[28:29], 0, v[230:231]
	v_lshl_add_u64 v[228:229], v[230:231], 0, v[228:229]
	s_waitcnt vmcnt(15)
	v_lshlrev_b32_e32 v248, 16, v244
	v_and_b32_e32 v249, 0xffff0000, v244
	v_lshlrev_b32_e32 v244, 16, v245
	v_and_b32_e32 v245, 0xffff0000, v245
	v_lshlrev_b32_e32 v250, 16, v246
	v_and_b32_e32 v251, 0xffff0000, v246
	v_lshlrev_b32_e32 v246, 16, v247
	v_and_b32_e32 v247, 0xffff0000, v247
	v_pk_add_f32 v[170:171], v[170:171], v[244:245]
	v_pk_add_f32 v[168:169], v[168:169], v[248:249]
	v_pk_add_f32 v[244:245], v[162:163], v[246:247]
	v_pk_add_f32 v[246:247], v[160:161], v[250:251]
	v_cvt_pk_bf16_f32 v160, v168, v169
	v_cvt_pk_bf16_f32 v161, v170, v171
	s_nop 0
	v_cvt_pk_bf16_f32 v162, v246, v247
	v_cvt_pk_bf16_f32 v163, v244, v245
	global_store_dwordx4 v[228:229], v[160:163], off
	s_nop 1
	v_mul_f32_e32 v160, v169, v169
	v_mul_f32_e32 v161, v171, v171
	v_fmac_f32_e32 v160, v168, v168
	v_fmac_f32_e32 v161, v170, v170
	v_add_f32_e32 v160, v160, v161
	v_mul_f32_e32 v161, v247, v247
	v_fmac_f32_e32 v161, v246, v246
	v_add_f32_e32 v160, v161, v160
	v_mul_f32_e32 v161, v245, v245
	v_fmac_f32_e32 v161, v244, v244
	v_add_f32_e32 v196, v161, v160
	s_waitcnt vmcnt(15)
	v_lshlrev_b32_e32 v160, 16, v192
	v_and_b32_e32 v161, 0xffff0000, v192
	v_lshlrev_b32_e32 v162, 16, v193
	v_and_b32_e32 v163, 0xffff0000, v193
	v_lshlrev_b32_e32 v168, 16, v194
	v_and_b32_e32 v169, 0xffff0000, v194
	v_lshlrev_b32_e32 v170, 16, v195
	v_and_b32_e32 v171, 0xffff0000, v195
	v_pk_add_f32 v[134:135], v[134:135], v[162:163]
	v_pk_add_f32 v[132:133], v[132:133], v[160:161]
	v_pk_add_f32 v[162:163], v[128:129], v[168:169]
	v_cvt_pk_bf16_f32 v128, v132, v133
	v_cvt_pk_bf16_f32 v129, v134, v135
	v_pk_add_f32 v[160:161], v[130:131], v[170:171]
	v_cvt_pk_bf16_f32 v130, v162, v163
	s_nop 0
	v_cvt_pk_bf16_f32 v131, v160, v161
	global_store_dwordx4 v[228:229], v[128:131], off offset:256
	s_nop 1
	v_mul_f32_e32 v128, v133, v133
	v_mul_f32_e32 v129, v135, v135
	v_fmac_f32_e32 v128, v132, v132
	v_fmac_f32_e32 v129, v134, v134
	v_add_f32_e32 v128, v128, v129
	v_mul_f32_e32 v129, v163, v163
	v_fmac_f32_e32 v129, v162, v162
	v_add_f32_e32 v128, v129, v128
	v_mul_f32_e32 v129, v161, v161
	v_fmac_f32_e32 v129, v160, v160
	v_and_b32_e32 v130, 64, v236
	v_add_f32_e32 v128, v129, v128
	v_xor_b32_e32 v129, 16, v236
	v_add_u32_e32 v131, 64, v130
	v_cmp_lt_i32_e32 vcc, v129, v131
	v_add_f32_e32 v128, v196, v128
	s_nop 0
	v_cndmask_b32_e32 v129, v236, v129, vcc
	v_lshlrev_b32_e32 v130, 2, v129
	ds_bpermute_b32 v129, v130, v128
	s_waitcnt lgkmcnt(0)
	v_add_f32_e32 v132, v128, v129
	v_xor_b32_e32 v128, 32, v236
	v_cmp_lt_i32_e32 vcc, v128, v131
	s_nop 1
	v_cndmask_b32_e32 v128, v236, v128, vcc
	v_lshlrev_b32_e32 v131, 2, v128
	ds_bpermute_b32 v133, v131, v132
	v_lshl_add_u64 v[128:129], v[226:227], 3, s[48:49]
	s_and_saveexec_b64 s[26:27], s[40:41]
	s_cbranch_execz .LBB0_179
	s_waitcnt lgkmcnt(0)
	v_add_f32_e32 v132, v132, v133
	v_mul_f32_e32 v132, 0x4b800000, v132
	v_trunc_f32_e32 v132, v132
	v_mul_f32_e32 v133, 0x2f800000, v132
	v_floor_f32_e32 v133, v133
	v_fmac_f32_e32 v132, 0xcf800000, v133
	v_cvt_u32_f32_e32 v132, v132
	v_cvt_u32_f32_e32 v133, v133
	global_atomic_add_x2 v[128:129], v[132:133], off
; __device__ __forceinline__ unsigned long long f2ss(float v) { return (unsigned long long)(v * 16777216.0f); }
; __device__ __forceinline__ u32x4 pack8(f32x4 v0, f32x4 v1) { u32x4 w; w.x = cvt_pk_bf16(v0[0], v0[1]); w.y = cvt_pk_bf16(v0[2], v0[3]); w.z = cvt_pk_bf16(v1[0], v1[1]); w.w = cvt_pk_bf16(v1[2], v1[3]); return w; }
;     __device__ __forceinline__ void operator()(const f32x4 (&acc)[2][2][4][2], const Unit& u, int wr, int wc, int fr, int fq, const Pre&) const {
;     ...
;             for (int m = 0; m < 4; ++m) { const int row = row0 + ai * HALF + m * 16; const size_t off = (size_t)row * 1024 + col0; float sq = 0.f;
; #pragma unroll
;                 for (int bj = 0; bj < 2; ++bj) { const u32x4 bw = bwv[ai][m][bj];
;                     const f32x4 b0 = (f32x4){__uint_as_float(bw.x << 16), __uint_as_float(bw.x & 0xffff0000u), __uint_as_float(bw.y << 16), __uint_as_float(bw.y & 0xffff0000u)};
;                     const f32x4 b1 = (f32x4){__uint_as_float(bw.z << 16), __uint_as_float(bw.z & 0xffff0000u), __uint_as_float(bw.w << 16), __uint_as_float(bw.w & 0xffff0000u)};
;                     const f32x4 v0 = acc[ai][bj][m][0] + b0, v1 = acc[ai][bj][m][1] + b1;
;                     *(gu32x4*)(hb + off + bj * HALF) = pack8(v0, v1);
;                     sq += (v0[0] * v0[0] + v0[1] * v0[1]) + (v0[2] * v0[2] + v0[3] * v0[3]) + (v1[0] * v1[0] + v1[1] * v1[1]) + (v1[2] * v1[2] + v1[3] * v1[3]); }
;                 sq += __shfl_xor(sq, 16); sq += __shfl_xor(sq, 32); if (fq == 0) atomicAdd(ssn + row, f2ss(sq)); }
.LBB0_179:
	s_or_b64 exec, exec, s[26:27]
	s_waitcnt vmcnt(15)
	v_lshlrev_b32_e32 v132, 16, v188
	s_waitcnt lgkmcnt(0)
	v_and_b32_e32 v133, 0xffff0000, v188
	v_lshlrev_b32_e32 v134, 16, v189
	v_and_b32_e32 v135, 0xffff0000, v189
	v_lshlrev_b32_e32 v160, 16, v190
	v_and_b32_e32 v161, 0xffff0000, v190
	v_pk_add_f32 v[108:109], v[108:109], v[132:133]
	v_pk_add_f32 v[110:111], v[110:111], v[134:135]
	v_pk_add_f32 v[134:135], v[104:105], v[160:161]
	v_cvt_pk_bf16_f32 v104, v108, v109
	v_mul_f32_e32 v109, v109, v109
	v_fmac_f32_e32 v109, v108, v108
	v_mul_f32_e32 v108, v111, v111
	v_fmac_f32_e32 v108, v110, v110
	v_lshlrev_b32_e32 v162, 16, v191
	v_and_b32_e32 v163, 0xffff0000, v191
	v_add_f32_e32 v108, v109, v108
	v_mul_f32_e32 v109, v135, v135
	v_pk_add_f32 v[132:133], v[106:107], v[162:163]
	v_fmac_f32_e32 v109, v134, v134
	v_add_f32_e32 v108, v109, v108
	v_mul_f32_e32 v109, v133, v133
	v_fmac_f32_e32 v109, v132, v132
	v_cvt_pk_bf16_f32 v105, v110, v111
	v_add_f32_e32 v160, v109, v108
	s_waitcnt vmcnt(14)
	v_lshlrev_b32_e32 v108, 16, v184
	v_and_b32_e32 v109, 0xffff0000, v184
	v_lshlrev_b32_e32 v110, 16, v185
	v_and_b32_e32 v111, 0xffff0000, v185
	v_cvt_pk_bf16_f32 v106, v134, v135
	v_cvt_pk_bf16_f32 v107, v132, v133
	v_lshlrev_b32_e32 v132, 16, v186
	v_and_b32_e32 v133, 0xffff0000, v186
	v_pk_add_f32 v[102:103], v[102:103], v[110:111]
	v_pk_add_f32 v[100:101], v[100:101], v[108:109]
	v_pk_add_f32 v[110:111], v[96:97], v[132:133]
	v_mul_f32_e32 v96, v101, v101
	v_mul_f32_e32 v97, v103, v103
	v_fmac_f32_e32 v96, v100, v100
	v_fmac_f32_e32 v97, v102, v102
	v_lshlrev_b32_e32 v134, 16, v187
	v_and_b32_e32 v135, 0xffff0000, v187
	v_add_f32_e32 v96, v96, v97
	v_mul_f32_e32 v97, v111, v111
	v_pk_add_f32 v[108:109], v[98:99], v[134:135]
	v_fmac_f32_e32 v97, v110, v110
	v_add_f32_e32 v96, v97, v96
	v_mul_f32_e32 v97, v109, v109
	v_fmac_f32_e32 v97, v108, v108
	v_add_f32_e32 v96, v97, v96
	v_add_f32_e32 v99, v160, v96
	ds_bpermute_b32 v134, v130, v99
	v_lshl_add_u64 v[96:97], s[28:29], 0, v[224:225]
	v_lshl_add_u64 v[132:133], v[210:211], 1, v[96:97]
	global_store_dwordx4 v[132:133], v[104:107], off
	v_cvt_pk_bf16_f32 v98, v100, v101
	s_waitcnt lgkmcnt(0)
	v_add_f32_e32 v96, v99, v134
	ds_bpermute_b32 v97, v131, v96
	v_cvt_pk_bf16_f32 v99, v102, v103
	v_cvt_pk_bf16_f32 v100, v110, v111
	v_cvt_pk_bf16_f32 v101, v108, v109
	global_store_dwordx4 v[132:133], v[98:101], off offset:256
	s_and_saveexec_b64 s[26:27], s[40:41]
	s_cbranch_execz .LBB0_181
	s_waitcnt lgkmcnt(0)
	v_add_f32_e32 v96, v96, v97
	v_mul_f32_e32 v96, 0x4b800000, v96
	v_trunc_f32_e32 v96, v96
	v_mul_f32_e32 v97, 0x2f800000, v96
	v_floor_f32_e32 v97, v97
	v_fmac_f32_e32 v96, 0xcf800000, v97
	v_cvt_u32_f32_e32 v96, v96
	v_cvt_u32_f32_e32 v97, v97
	global_atomic_add_x2 v[128:129], v[96:97], off offset:128

; __device__ __forceinline__ unsigned long long f2ss(float v) { return (unsigned long long)(v * 16777216.0f); }
; __device__ __forceinline__ u32x4 pack8(f32x4 v0, f32x4 v1) { u32x4 w; w.x = cvt_pk_bf16(v0[0], v0[1]); w.y = cvt_pk_bf16(v0[2], v0[3]); w.z = cvt_pk_bf16(v1[0], v1[1]); w.w = cvt_pk_bf16(v1[2], v1[3]); return w; }
;     __device__ __forceinline__ void operator()(const f32x4 (&acc)[2][2][4][2], const Unit& u, int wr, int wc, int fr, int fq, const Pre&) const {
;     ...
;             for (int m = 0; m < 4; ++m) { const int row = row0 + ai * HALF + m * 16; const size_t off = (size_t)row * 1024 + col0; float sq = 0.f;
; #pragma unroll
;                 for (int bj = 0; bj < 2; ++bj) { const u32x4 bw = bwv[ai][m][bj];
;                     const f32x4 b0 = (f32x4){__uint_as_float(bw.x << 16), __uint_as_float(bw.x & 0xffff0000u), __uint_as_float(bw.y << 16), __uint_as_float(bw.y & 0xffff0000u)};
;                     const f32x4 b1 = (f32x4){__uint_as_float(bw.z << 16), __uint_as_float(bw.z & 0xffff0000u), __uint_as_float(bw.w << 16), __uint_as_float(bw.w & 0xffff0000u)};
;                     const f32x4 v0 = acc[ai][bj][m][0] + b0, v1 = acc[ai][bj][m][1] + b1;
;                     *(gu32x4*)(hb + off + bj * HALF) = pack8(v0, v1);
;                     sq += (v0[0] * v0[0] + v0[1] * v0[1]) + (v0[2] * v0[2] + v0[3] * v0[3]) + (v1[0] * v1[0] + v1[1] * v1[1]) + (v1[2] * v1[2] + v1[3] * v1[3]); }
;                 sq += __shfl_xor(sq, 16); sq += __shfl_xor(sq, 32); if (fq == 0) atomicAdd(ssn + row, f2ss(sq)); }
.LBB0_187:
	s_or_b64 exec, exec, s[26:27]
	s_waitcnt vmcnt(15)
	v_lshlrev_b32_e32 v48, 16, v140
	s_waitcnt lgkmcnt(0)
	v_and_b32_e32 v49, 0xffff0000, v140
	v_lshlrev_b32_e32 v50, 16, v141
	v_and_b32_e32 v51, 0xffff0000, v141
	v_lshlrev_b32_e32 v52, 16, v142
	v_and_b32_e32 v53, 0xffff0000, v142
	v_pk_add_f32 v[44:45], v[44:45], v[48:49]
	v_pk_add_f32 v[46:47], v[46:47], v[50:51]
	v_pk_add_f32 v[50:51], v[40:41], v[52:53]
	v_cvt_pk_bf16_f32 v40, v44, v45
	v_mul_f32_e32 v45, v45, v45
	v_fmac_f32_e32 v45, v44, v44
	v_mul_f32_e32 v44, v47, v47
	v_fmac_f32_e32 v44, v46, v46
	v_lshlrev_b32_e32 v54, 16, v143
	v_and_b32_e32 v55, 0xffff0000, v143
	v_add_f32_e32 v44, v45, v44
	v_mul_f32_e32 v45, v51, v51
	v_pk_add_f32 v[48:49], v[42:43], v[54:55]
	v_fmac_f32_e32 v45, v50, v50
	v_add_f32_e32 v44, v45, v44
	v_mul_f32_e32 v45, v49, v49
	v_fmac_f32_e32 v45, v48, v48
	v_cvt_pk_bf16_f32 v41, v46, v47
	v_add_f32_e32 v52, v45, v44
	s_waitcnt vmcnt(14)
	v_lshlrev_b32_e32 v44, 16, v136
	v_and_b32_e32 v45, 0xffff0000, v136
	v_lshlrev_b32_e32 v46, 16, v137
	v_and_b32_e32 v47, 0xffff0000, v137
	v_cvt_pk_bf16_f32 v42, v50, v51
	v_cvt_pk_bf16_f32 v43, v48, v49
	v_lshlrev_b32_e32 v48, 16, v138
	v_and_b32_e32 v49, 0xffff0000, v138
	v_pk_add_f32 v[38:39], v[38:39], v[46:47]
	v_pk_add_f32 v[36:37], v[36:37], v[44:45]
	v_pk_add_f32 v[46:47], v[32:33], v[48:49]
	v_mul_f32_e32 v32, v37, v37
	v_mul_f32_e32 v33, v39, v39
	v_fmac_f32_e32 v32, v36, v36
	v_fmac_f32_e32 v33, v38, v38
	v_lshlrev_b32_e32 v50, 16, v139
	v_and_b32_e32 v51, 0xffff0000, v139
	v_add_f32_e32 v32, v32, v33
	v_mul_f32_e32 v33, v47, v47
	v_pk_add_f32 v[44:45], v[34:35], v[50:51]
	v_fmac_f32_e32 v33, v46, v46
	v_add_f32_e32 v32, v33, v32
	v_mul_f32_e32 v33, v45, v45
	v_fmac_f32_e32 v33, v44, v44
	v_add_f32_e32 v32, v33, v32
	v_add_f32_e32 v35, v52, v32
	ds_bpermute_b32 v50, v130, v35
	v_lshl_add_u64 v[32:33], s[28:29], 0, v[216:217]
	v_lshl_add_u64 v[48:49], v[210:211], 1, v[32:33]
	global_store_dwordx4 v[48:49], v[40:43], off
	v_cvt_pk_bf16_f32 v34, v36, v37
	s_waitcnt lgkmcnt(0)
	v_add_f32_e32 v32, v35, v50
	ds_bpermute_b32 v33, v131, v32
	v_cvt_pk_bf16_f32 v35, v38, v39
	v_cvt_pk_bf16_f32 v36, v46, v47
	v_cvt_pk_bf16_f32 v37, v44, v45
	global_store_dwordx4 v[48:49], v[34:37], off offset:256
	s_and_saveexec_b64 s[26:27], s[40:41]
	s_cbranch_execz .LBB0_189
	s_waitcnt lgkmcnt(0)
	v_add_f32_e32 v32, v32, v33
	v_mul_f32_e32 v32, 0x4b800000, v32
	v_trunc_f32_e32 v32, v32
	v_mul_f32_e32 v33, 0x2f800000, v32
	v_floor_f32_e32 v33, v33
	v_fmac_f32_e32 v32, 0xcf800000, v33
	v_cvt_u32_f32_e32 v32, v32
	v_cvt_u32_f32_e32 v33, v33
	global_atomic_add_x2 v[128:129], v[32:33], off offset:1152
